# slot quota 20 transpose items per wave + latent-first hyena ordering
# baseline (speedup 1.0000x reference)
.LBB0_130:
	s_or_b64 exec, exec, s[0:1]
	s_load_dwordx2 s[0:1], s[92:93], 0x58
	s_load_dwordx2 s[2:3], s[92:93], 0xb8
	s_load_dwordx2 s[4:5], s[92:93], 0xc0
	s_load_dwordx2 s[6:7], s[92:93], 0xc8
	s_load_dwordx2 s[8:9], s[92:93], 0xd0
	s_load_dwordx2 s[10:11], s[92:93], 0xe8
	v_and_b32_e32 v74, 63, v154
	v_lshrrev_b32_e32 v75, 6, v154
	v_mul_u32_u24_e32 v75, 0x2100, v75
	v_lshrrev_b32_e32 v3, 5, v74
	v_and_b32_e32 v4, 31, v74
	v_lshlrev_b32_e32 v4, 2, v4
	v_lshrrev_b32_e32 v5, 3, v74
	v_and_b32_e32 v6, 7, v74
	v_mul_u32_u24_e32 v2, 264, v6
	v_add_u32_e32 v2, v2, v5
	v_lshl_add_u32 v2, v2, 2, v75
	v_lshlrev_b32_e32 v6, 4, v6
	v_mul_u32_u24_e32 v1, 132, v5
	v_add3_u32 v1, v1, v6, v75
	v_readfirstlane_b32 s13, v154
	s_lshr_b32 s13, s13, 6
	s_lshl_b32 s26, s96, 3
	s_add_u32 s13, s13, s26
	s_mov_b32 s12, s13
	s_waitcnt lgkmcnt(0)
	s_cmp_ge_u32 s12, 46080
	s_cbranch_scc1 .Ltra_done
	s_cmp_ge_u32 s12, 33280
	s_cselect_b32 s41, 1, 0
	s_cselect_b32 s26, 33280, 0
	s_sub_u32 s42, s12, s26
	s_cmp_ge_u32 s42, 12288
	s_cbranch_scc1 .Ltra_m2
	s_mul_i32 s43, s42, 43691
	s_lshr_b32 s43, s43, 24
	s_mul_i32 s26, s43, 384
	s_sub_u32 s44, s42, s26
	s_mov_b32 s14, s0
	s_mov_b32 s15, s1
	s_mov_b32 s36, 0xc000
	s_mov_b32 s37, 0x6000000
	s_mov_b32 s38, 0x0
	s_mov_b32 s39, 0x3000000
	s_mov_b32 s40, 0x1000
	s_branch .Ltra_dec_done1

.Ltra_loop:
	s_add_u32 s12, s12, 2048
	s_cmp_lt_u32 s12, 46080
	s_cselect_b32 s24, 1, 0
	s_cbranch_scc0 .Ltra_nonext8
	s_cmp_ge_u32 s12, 33280
	s_cselect_b32 s41, 1, 0
	s_cselect_b32 s26, 33280, 0
	s_sub_u32 s42, s12, s26
	s_cmp_ge_u32 s42, 12288
	s_cbranch_scc1 .Ltra_m11
	s_mul_i32 s43, s42, 43691
	s_lshr_b32 s43, s43, 24
	s_mul_i32 s26, s43, 384
	s_sub_u32 s44, s42, s26
	s_mov_b32 s16, s0
	s_mov_b32 s17, s1
	s_mov_b32 s36, 0xc000
	s_mov_b32 s37, 0x6000000
	s_mov_b32 s38, 0x0
	s_mov_b32 s39, 0x3000000
	s_mov_b32 s40, 0x1000
	s_branch .Ltra_dec_done10

.Ltra_after9:
	ds_write_b32 v1, v10 offset:0
	ds_write_b32 v1, v11 offset:4
	ds_write_b32 v1, v12 offset:8
	ds_write_b32 v1, v13 offset:12
	ds_write_b32 v1, v14 offset:1056
	ds_write_b32 v1, v15 offset:1060
	ds_write_b32 v1, v16 offset:1064
	ds_write_b32 v1, v17 offset:1068
	ds_write_b32 v1, v18 offset:2112
	ds_write_b32 v1, v19 offset:2116
	ds_write_b32 v1, v20 offset:2120
	ds_write_b32 v1, v21 offset:2124
	ds_write_b32 v1, v22 offset:3168
	ds_write_b32 v1, v23 offset:3172
	ds_write_b32 v1, v24 offset:3176
	ds_write_b32 v1, v25 offset:3180
	ds_write_b32 v1, v26 offset:4224
	ds_write_b32 v1, v27 offset:4228
	ds_write_b32 v1, v28 offset:4232
	ds_write_b32 v1, v29 offset:4236
	ds_write_b32 v1, v30 offset:5280
	ds_write_b32 v1, v31 offset:5284
	ds_write_b32 v1, v32 offset:5288
	ds_write_b32 v1, v33 offset:5292
	ds_write_b32 v1, v34 offset:6336
	ds_write_b32 v1, v35 offset:6340
	ds_write_b32 v1, v36 offset:6344
	ds_write_b32 v1, v37 offset:6348
	ds_write_b32 v1, v38 offset:7392
	ds_write_b32 v1, v39 offset:7396
	ds_write_b32 v1, v40 offset:7400
	ds_write_b32 v1, v41 offset:7404
	v_mad_u32_u24 v9, v5, s22, v6
	s_lshl_b32 s46, s22, 3
	s_waitcnt lgkmcnt(0)
	ds_read_b32 v74, v2 offset:0
	ds_read_b32 v75, v2 offset:132
	ds_read_b32 v76, v2 offset:264
	ds_read_b32 v77, v2 offset:396
	ds_read_b32 v78, v2 offset:528
	ds_read_b32 v79, v2 offset:660
	ds_read_b32 v80, v2 offset:792
	ds_read_b32 v81, v2 offset:924
	ds_read_b32 v82, v2 offset:32
	ds_read_b32 v83, v2 offset:164
	ds_read_b32 v84, v2 offset:296
	ds_read_b32 v85, v2 offset:428
	ds_read_b32 v86, v2 offset:560
	ds_read_b32 v87, v2 offset:692
	ds_read_b32 v88, v2 offset:824
	ds_read_b32 v89, v2 offset:956
	s_waitcnt lgkmcnt(8)
	v_cvt_pk_bf16_f32 v106, v74, v75
	v_cvt_pk_bf16_f32 v107, v76, v77
	v_cvt_pk_bf16_f32 v108, v78, v79
	v_cvt_pk_bf16_f32 v109, v80, v81
	global_store_dwordx4 v9, v[106:109], s[18:19]
	s_add_u32 s18, s18, s46
	s_addc_u32 s19, s19, 0
	ds_read_b32 v90, v2 offset:64
	ds_read_b32 v91, v2 offset:196
	ds_read_b32 v92, v2 offset:328
	ds_read_b32 v93, v2 offset:460
	ds_read_b32 v94, v2 offset:592
	ds_read_b32 v95, v2 offset:724
	ds_read_b32 v96, v2 offset:856
	ds_read_b32 v97, v2 offset:988
	s_waitcnt lgkmcnt(8)
	v_cvt_pk_bf16_f32 v110, v82, v83
	v_cvt_pk_bf16_f32 v111, v84, v85
	v_cvt_pk_bf16_f32 v112, v86, v87
	v_cvt_pk_bf16_f32 v113, v88, v89
	global_store_dwordx4 v9, v[110:113], s[18:19]
	s_add_u32 s18, s18, s46
	s_addc_u32 s19, s19, 0
	ds_read_b32 v98, v2 offset:96
	ds_read_b32 v99, v2 offset:228
	ds_read_b32 v100, v2 offset:360
	ds_read_b32 v101, v2 offset:492
	ds_read_b32 v102, v2 offset:624
	ds_read_b32 v103, v2 offset:756
	ds_read_b32 v104, v2 offset:888
	ds_read_b32 v105, v2 offset:1020
	s_waitcnt lgkmcnt(8)
	v_cvt_pk_bf16_f32 v106, v90, v91
	v_cvt_pk_bf16_f32 v107, v92, v93
	v_cvt_pk_bf16_f32 v108, v94, v95
	v_cvt_pk_bf16_f32 v109, v96, v97
	global_store_dwordx4 v9, v[106:109], s[18:19]
	s_add_u32 s18, s18, s46
	s_addc_u32 s19, s19, 0
	s_waitcnt lgkmcnt(0)
	v_cvt_pk_bf16_f32 v110, v98, v99
	v_cvt_pk_bf16_f32 v111, v100, v101
	v_cvt_pk_bf16_f32 v112, v102, v103
	v_cvt_pk_bf16_f32 v113, v104, v105
	global_store_dwordx4 v9, v[110:113], s[18:19]
	s_cmp_eq_u32 s24, 0
	s_cbranch_scc1 .Ltra_done
	s_add_u32 s12, s12, 2048
	s_cmp_lt_u32 s12, 46080
	s_cselect_b32 s24, 1, 0
	s_cbranch_scc0 .Ltra_nonext17
	s_cmp_ge_u32 s12, 33280
	s_cselect_b32 s41, 1, 0
	s_cselect_b32 s26, 33280, 0
	s_sub_u32 s42, s12, s26
	s_cmp_ge_u32 s42, 12288
	s_cbranch_scc1 .Ltra_m20
	s_mul_i32 s43, s42, 43691
	s_lshr_b32 s43, s43, 24
	s_mul_i32 s26, s43, 384
	s_sub_u32 s44, s42, s26
	s_mov_b32 s14, s0
	s_mov_b32 s15, s1
	s_mov_b32 s36, 0xc000
	s_mov_b32 s37, 0x6000000
	s_mov_b32 s38, 0x0
	s_mov_b32 s39, 0x3000000
	s_mov_b32 s40, 0x1000
	s_branch .Ltra_dec_done19

.LBB0_1179:
	s_waitcnt vmcnt(0)
	s_barrier
	s_cmp_lt_u32 s96, 128
	s_cbranch_scc1 .LBB0_1180
	s_load_dwordx2 s[0:1], s[92:93], 0x58
	s_load_dwordx2 s[2:3], s[92:93], 0xb8
	s_load_dwordx2 s[4:5], s[92:93], 0xc0
	s_load_dwordx2 s[6:7], s[92:93], 0xc8
	s_load_dwordx2 s[8:9], s[92:93], 0xd0
	s_load_dwordx2 s[10:11], s[92:93], 0xe8
	v_and_b32_e32 v74, 63, v154
	v_lshrrev_b32_e32 v75, 6, v154
	v_mul_u32_u24_e32 v75, 0x2100, v75
	v_lshrrev_b32_e32 v3, 5, v74
	v_and_b32_e32 v4, 31, v74
	v_lshlrev_b32_e32 v4, 2, v4
	v_lshrrev_b32_e32 v5, 3, v74
	v_and_b32_e32 v6, 7, v74
	v_mul_u32_u24_e32 v2, 264, v6
	v_add_u32_e32 v2, v2, v5
	v_lshl_add_u32 v2, v2, 2, v75
	v_lshlrev_b32_e32 v6, 4, v6
	v_mul_u32_u24_e32 v1, 132, v5
	v_add3_u32 v1, v1, v6, v75
	v_readfirstlane_b32 s13, v154
	s_lshr_b32 s13, s13, 6
	s_lshl_b32 s26, s96, 3
	s_add_u32 s13, s13, s26
	s_sub_u32 s12, s13, 1024
	s_add_u32 s12, s12, 46080
	s_waitcnt lgkmcnt(0)
	s_cmp_ge_u32 s12, 66560
	s_cbranch_scc1 .Ltrs_done
	s_cmp_ge_u32 s12, 33280
	s_cselect_b32 s41, 1, 0
	s_cselect_b32 s26, 33280, 0
	s_sub_u32 s42, s12, s26
	s_cmp_ge_u32 s42, 12288
	s_cbranch_scc1 .Ltrs_m2
	s_mul_i32 s43, s42, 43691
	s_lshr_b32 s43, s43, 24
	s_mul_i32 s26, s43, 384
	s_sub_u32 s44, s42, s26
	s_mov_b32 s14, s0
	s_mov_b32 s15, s1
	s_mov_b32 s36, 0xc000
	s_mov_b32 s37, 0x6000000
	s_mov_b32 s38, 0x0
	s_mov_b32 s39, 0x3000000
	s_mov_b32 s40, 0x1000
	s_branch .Ltrs_dec_done1
